# layout variant of v95: entry shift 13 dwords instead of 9 (same code)
# speedup vs baseline: 1.0112x; 1.0056x over previous
; #define LAS __attribute__((address_space(3)))
; __global__ void __launch_bounds__(512, 2) mega(Params P, int ph0, int ph1) {
;     extern __shared__ __attribute__((aligned(16))) unsigned char shm[];
;     __shared__ uint4 xb_words;
;     if (threadIdx.x == 0) xb_words = make_uint4(0u, 0u, 0u, 0u);
;     __syncthreads();
;     const XcdBarrier xb = xcd_barrier_post((unsigned*)(P.ws + O_BAR), (volatile LAS unsigned*)&xb_words);
_Z4mega6Paramsii:
	s_nop 0
	s_nop 0
	s_nop 0
	s_nop 0
	s_nop 0
	s_nop 0
	s_nop 0
	s_nop 0
	s_nop 0
	s_nop 0
	s_nop 0
	s_nop 0
	s_nop 0
	s_load_dwordx2 s[88:89], s[0:1], 0xd0
	s_mov_b32 s84, s2
	s_mov_b64 s[86:87], s[0:1]
	v_cmp_eq_u32_e64 s[92:93], 0, v0
	s_and_saveexec_b64 s[4:5], s[92:93]
	v_mov_b32_e32 v2, 0
	v_mov_b32_e32 v3, v2
	v_mov_b32_e32 v4, v2
	v_mov_b32_e32 v5, v2
	ds_write_b128 v2, v[2:5]
	s_or_b64 exec, exec, s[4:5]
	s_waitcnt lgkmcnt(0)
	s_barrier
	s_add_u32 s90, s88, 0x2e9d8000
	s_getreg_b32 s0, hwreg(HW_REG_XCC_ID, 0, 4)
	s_addc_u32 s91, s89, 0
	s_and_b32 s85, s0, 15
	s_and_saveexec_b64 s[4:5], s[92:93]
	s_cbranch_execz .LBB0_5
	s_mov_b64 s[6:7], exec
	v_mbcnt_lo_u32_b32 v1, s6, 0
	v_mbcnt_hi_u32_b32 v1, s7, v1
	v_cmp_eq_u32_e32 vcc, 0, v1
	s_and_b64 s[0:1], exec, vcc
	s_mov_b64 exec, s[0:1]
	s_cbranch_execz .LBB0_5
	s_lshl_b32 s0, s85, 8
	s_bcnt1_i32_b64 s1, s[6:7]
	v_mov_b32_e32 v1, s0
	v_mov_b32_e32 v2, s1
	global_atomic_add v1, v2, s[90:91] offset:1024
